# gate/up GEMM: first two K-loop waits of a tile allow the previous tile's 8 stores in flight (vmcnt 16 instead of 8, strategy 1 counted waits)
# baseline (speedup 1.0000x reference)
.LBB0_1092:
	s_or_b64 exec, exec, s[0:1]
	s_mov_b32 s101, 0
	v_mov_b32_e32 v10, v193
	s_waitcnt lgkmcnt(0)
	s_barrier
	s_cmpk_gt_i32 s6, 0xaff
	v_readfirstlane_b32 s0, v10
	s_cbranch_scc1 .LBB0_1108
	v_lshlrev_b32_e32 v0, 4, v10
	v_add_u32_e32 v1, 0x2000, v0
	v_ashrrev_i32_e32 v2, 31, v1
	v_lshrrev_b32_e32 v2, 22, v2
	v_add_u32_e32 v2, v1, v2
	v_ashrrev_i32_e32 v8, 10, v2
	v_mul_i32_i24_e32 v2, 0x400, v8
	v_sub_u32_e32 v1, v1, v2
	v_lshrrev_b32_e32 v2, 4, v1
	v_bitop3_b32 v1, v2, v1, 32 bitop3:0x6c
	v_ashrrev_i32_e32 v2, 31, v1
	v_lshrrev_b32_e32 v2, 26, v2
	v_add_u32_e32 v2, v1, v2
	v_lshlrev_b32_e32 v3, 3, v8
	v_ashrrev_i32_e32 v9, 6, v2
	v_and_b32_e32 v3, -16, v3
	v_add_u32_e32 v3, v9, v3
	v_and_b32_e32 v4, 3, v9
	s_mov_b32 s3, 0x1fffe0
	v_lshrrev_b32_e32 v5, 2, v3
	v_lshlrev_b32_e32 v6, 1, v3
	v_and_b32_e32 v2, 0xc0, v2
	v_and_or_b32 v4, v3, s3, v4
	v_and_b32_e32 v5, 4, v5
	v_and_b32_e32 v6, 24, v6
	v_sub_u32_e32 v1, v1, v2
	v_mov_b32_e32 v2, 1
	v_or3_b32 v4, v4, v5, v6
	v_lshlrev_b32_e32 v5, 5, v8
	v_ashrrev_i16_sdwa v1, v2, sext(v1) dst_sel:DWORD dst_unused:UNUSED_PAD src0_sel:DWORD src1_sel:BYTE_0
	v_and_b32_e32 v5, 32, v5
	v_bfe_i32 v11, v1, 0, 16
	v_add_lshl_u32 v1, v5, v11, 1
	v_lshl_add_u32 v128, v4, 11, v1
	v_lshl_add_u32 v130, v3, 11, v1
	v_bfe_i32 v1, v10, 27, 1
	v_lshrrev_b32_e32 v1, 22, v1
	v_add_u32_e32 v1, v0, v1
	v_and_b32_e32 v1, 0xfffffc00, v1
	v_sub_u32_e32 v0, v0, v1
	v_lshrrev_b32_e32 v1, 4, v0
	v_ashrrev_i32_e32 v3, 31, v10
	v_bitop3_b32 v0, v1, v0, 32 bitop3:0x6c
	v_lshrrev_b32_e32 v3, 26, v3
	v_ashrrev_i32_e32 v1, 31, v0
	v_add_u32_e32 v3, v10, v3
	v_lshrrev_b32_e32 v1, 26, v1
	v_ashrrev_i32_e32 v13, 6, v3
	v_add_u32_e32 v1, v0, v1
	v_lshlrev_b32_e32 v3, 3, v13
	v_ashrrev_i32_e32 v12, 6, v1
	v_and_b32_e32 v3, -16, v3
	v_add_u32_e32 v3, v12, v3
	v_and_b32_e32 v4, 3, v12
	v_and_or_b32 v4, v3, s3, v4
	s_ashr_i32 s3, s6, 31
	s_lshr_b32 s7, s3, 29
	s_add_i32 s7, s6, s7
	s_ashr_i32 s12, s0, 6
	s_ashr_i32 s8, s7, 3
	s_and_b32 s7, s7, -8
	s_ashr_i32 s1, s0, 8
	s_lshl_b32 s2, s12, 10
	s_sub_i32 s9, s6, s7
	s_cmp_lt_i32 s9, 0
	s_movk_i32 s7, 0x161
	s_cselect_b32 s13, s7, 0x160
	s_mul_i32 s9, s9, s13
	s_add_i32 s9, s9, s8
	s_mul_hi_i32 s8, s9, 0x2e8ba2e9
	s_lshr_b32 s13, s8, 31
	s_ashr_i32 s8, s8, 5
	s_add_i32 s8, s8, s13
	s_mul_i32 s13, s8, 0xb0
	s_sub_i32 s9, s9, s13
	s_sext_i32_i16 s13, s9
	s_bfe_u32 s13, s13, 0x3001c
	s_add_i32 s13, s9, s13
	s_sext_i32_i16 s24, s13
	s_and_b32 s13, s13, 0xfff8
	s_sub_i32 s9, s9, s13
	s_sext_i32_i16 s9, s9
	s_lshl_b32 s8, s8, 11
	s_lshl_b32 s9, s9, 8
	s_add_i32 s38, s9, s8
	s_lshl_b32 s8, s24, 5
	s_ashr_i32 s39, s38, 31
	s_and_b32 s40, s8, 0xffffff00
	s_lshl_b64 s[8:9], s[38:39], 11
	v_lshrrev_b32_e32 v5, 2, v3
	v_lshlrev_b32_e32 v6, 1, v3
	v_and_b32_e32 v1, 0xc0, v1
	s_add_u32 s42, s18, s8
	v_and_b32_e32 v5, 4, v5
	v_and_b32_e32 v6, 24, v6
	v_sub_u32_e32 v0, v0, v1
	s_addc_u32 s43, s19, s9
	s_ashr_i32 s41, s40, 31
	v_or3_b32 v4, v4, v5, v6
	v_lshlrev_b32_e32 v5, 5, v13
	v_ashrrev_i16_sdwa v0, v2, sext(v0) dst_sel:DWORD dst_unused:UNUSED_PAD src0_sel:DWORD src1_sel:BYTE_0
	s_lshl_b64 s[8:9], s[40:41], 11
	v_and_b32_e32 v5, 32, v5
	v_bfe_i32 v14, v0, 0, 16
	s_add_u32 s44, s16, s8
	v_add_lshl_u32 v0, v5, v14, 1
	s_addc_u32 s45, s17, s9
	s_add_i32 s33, s2, 0
	v_lshl_add_u32 v132, v4, 11, v0
	s_add_i32 m0, s33, 0x10000
	v_lshl_add_u32 v134, v3, 11, v0
	global_load_lds_dwordx4 v132, s[44:45]
	s_add_i32 m0, s33, 0x12000
	s_add_u32 s8, s44, 0x40000
	global_load_lds_dwordx4 v128, s[44:45]
	s_addc_u32 s9, s45, 0
	s_add_i32 m0, s33, 0x14000
	s_add_i32 s34, s33, 0x2000
	global_load_lds_dwordx4 v132, s[8:9]
	s_add_i32 m0, s33, 0x16000
	v_mov_b32_e32 v137, 0
	global_load_lds_dwordx4 v128, s[8:9]
	s_mov_b32 m0, s33
	s_add_u32 s8, s42, 0x40000
	global_load_lds_dwordx4 v134, s[42:43]
	s_mov_b32 m0, s34
	s_addc_u32 s9, s43, 0
	s_add_i32 s35, s33, 0x4000
	global_load_lds_dwordx4 v130, s[42:43]
	s_mov_b32 m0, s35
	s_add_i32 s39, s33, 0x6000
	global_load_lds_dwordx4 v134, s[8:9]
	s_mov_b32 m0, s39
	v_mov_b32_e32 v133, v137
	global_load_lds_dwordx4 v130, s[8:9]
	v_mov_b32_e32 v129, v137
	v_mov_b32_e32 v135, v137
	v_mov_b32_e32 v131, v137
	s_cmp_eq_u32 s1, 1
	s_mov_b32 s41, 0
	v_lshl_add_u64 v[6:7], s[44:45], 0, v[132:133]
	v_lshl_add_u64 v[4:5], s[44:45], 0, v[128:129]
	v_lshl_add_u64 v[0:1], s[42:43], 0, v[134:135]
	s_cselect_b64 s[8:9], -1, 0
	s_cmp_lg_u32 s1, 1
	v_lshl_add_u64 v[2:3], s[42:43], 0, v[130:131]
	s_cbranch_scc1 .LBB0_1095
	s_barrier

.LBB0_1101:
	ds_read_b128 v[156:159], v153
	ds_read_b128 v[160:163], v153 offset:1024
	ds_read_b128 v[164:167], v153 offset:2048
	ds_read_b128 v[168:171], v153 offset:3072
	ds_read_b128 v[172:175], v154
	ds_read_b128 v[176:179], v154 offset:1024
	ds_read_b128 v[180:183], v154 offset:2048
	ds_read_b128 v[184:187], v154 offset:3072
	s_add_u32 s44, s42, 0xfffc0080
	s_addc_u32 s45, s43, -1
	s_cmp_eq_u32 s55, 12
	s_cselect_b32 s47, s31, s45
	s_cselect_b32 s46, s30, s44
	s_cselect_b32 s45, s37, s29
	s_cselect_b32 s44, s36, s27
	v_lshl_add_u64 v[148:149], s[42:43], 0, v[138:139]
	s_add_i32 m0, s33, 0xc000
	ds_read_b128 v[188:191], v155
	ds_read_b128 v[194:197], v155 offset:1024
	ds_read_b128 v[198:201], v155 offset:2048
	ds_read_b128 v[202:205], v155 offset:3072
	ds_read_b128 v[206:209], v155 offset:4096
	ds_read_b128 v[210:213], v155 offset:5120
	ds_read_b128 v[214:217], v155 offset:6144
	ds_read_b128 v[218:221], v155 offset:7168
	global_load_lds_dwordx4 v[148:149], off
	v_lshl_add_u64 v[148:149], s[42:43], 0, v[140:141]
	s_add_i32 m0, s33, 0xe000
	s_nop 0
	global_load_lds_dwordx4 v[148:149], off
	s_cmp_eq_u32 s101, 0
	s_cbranch_scc1 .Lxw_p10_1s
	s_waitcnt vmcnt(16)
	s_branch .Lxw_p10_1j
.Lxw_p10_1s:
	s_waitcnt vmcnt(8)
.Lxw_p10_1j:
	s_waitcnt lgkmcnt(0)
	s_barrier
	s_setprio 1
	s_waitcnt lgkmcnt(0)
	v_mfma_f32_16x16x32_bf16 v[124:127], v[156:159], v[188:191], v[124:127]
	v_mfma_f32_16x16x32_bf16 v[120:123], v[164:167], v[188:191], v[120:123]
	v_mfma_f32_16x16x32_bf16 v[108:111], v[156:159], v[198:201], v[108:111]
	v_mfma_f32_16x16x32_bf16 v[104:107], v[164:167], v[198:201], v[104:107]
	v_mfma_f32_16x16x32_bf16 v[92:95], v[156:159], v[206:209], v[92:95]
	v_mfma_f32_16x16x32_bf16 v[88:91], v[164:167], v[206:209], v[88:91]
	v_mfma_f32_16x16x32_bf16 v[76:79], v[156:159], v[214:217], v[76:79]
	v_mfma_f32_16x16x32_bf16 v[72:75], v[164:167], v[214:217], v[72:75]
	v_mfma_f32_16x16x32_bf16 v[124:127], v[160:163], v[194:197], v[124:127]
	v_mfma_f32_16x16x32_bf16 v[120:123], v[168:171], v[194:197], v[120:123]
	v_mfma_f32_16x16x32_bf16 v[108:111], v[160:163], v[202:205], v[108:111]
	v_mfma_f32_16x16x32_bf16 v[104:107], v[168:171], v[202:205], v[104:107]
	v_mfma_f32_16x16x32_bf16 v[92:95], v[160:163], v[210:213], v[92:95]
	v_mfma_f32_16x16x32_bf16 v[88:91], v[168:171], v[210:213], v[88:91]
	v_mfma_f32_16x16x32_bf16 v[76:79], v[160:163], v[218:221], v[76:79]
	v_mfma_f32_16x16x32_bf16 v[72:75], v[168:171], v[218:221], v[72:75]
	v_mfma_f32_16x16x32_bf16 v[116:119], v[172:175], v[188:191], v[116:119]
	v_mfma_f32_16x16x32_bf16 v[112:115], v[180:183], v[188:191], v[112:115]
	v_mfma_f32_16x16x32_bf16 v[100:103], v[172:175], v[198:201], v[100:103]
	v_mfma_f32_16x16x32_bf16 v[96:99], v[180:183], v[198:201], v[96:99]
	v_mfma_f32_16x16x32_bf16 v[84:87], v[172:175], v[206:209], v[84:87]
	v_mfma_f32_16x16x32_bf16 v[80:83], v[180:183], v[206:209], v[80:83]
	v_mfma_f32_16x16x32_bf16 v[68:71], v[172:175], v[214:217], v[68:71]
	v_mfma_f32_16x16x32_bf16 v[64:67], v[180:183], v[214:217], v[64:67]
	v_mfma_f32_16x16x32_bf16 v[116:119], v[176:179], v[194:197], v[116:119]
	v_mfma_f32_16x16x32_bf16 v[112:115], v[184:187], v[194:197], v[112:115]
	v_mfma_f32_16x16x32_bf16 v[100:103], v[176:179], v[202:205], v[100:103]
	v_mfma_f32_16x16x32_bf16 v[96:99], v[184:187], v[202:205], v[96:99]
	v_mfma_f32_16x16x32_bf16 v[84:87], v[176:179], v[210:213], v[84:87]
	v_mfma_f32_16x16x32_bf16 v[80:83], v[184:187], v[210:213], v[80:83]
	v_mfma_f32_16x16x32_bf16 v[68:71], v[176:179], v[218:221], v[68:71]
	v_mfma_f32_16x16x32_bf16 v[64:67], v[184:187], v[218:221], v[64:67]
	s_setprio 0
	s_barrier
	s_add_i32 s56, s52, s2
	v_lshl_add_u64 v[148:149], s[44:45], 0, v[132:133]
	s_mov_b32 m0, s56
	ds_read_b128 v[188:191], v155 offset:16384
	ds_read_b128 v[194:197], v155 offset:17408
	ds_read_b128 v[198:201], v155 offset:18432
	ds_read_b128 v[202:205], v155 offset:19456
	ds_read_b128 v[206:209], v155 offset:20480
	ds_read_b128 v[210:213], v155 offset:21504
	ds_read_b128 v[214:217], v155 offset:22528
	ds_read_b128 v[218:221], v155 offset:23552
	global_load_lds_dwordx4 v[148:149], off
	s_add_i32 m0, s56, 0x2000
	s_add_u32 s56, s44, 0x40000
	v_lshl_add_u64 v[222:223], s[44:45], 0, v[128:129]
	s_addc_u32 s57, s45, 0
	s_add_i32 s58, s53, s2
	global_load_lds_dwordx4 v[222:223], off
	v_lshl_add_u64 v[224:225], s[56:57], 0, v[132:133]
	s_mov_b32 m0, s58
	v_lshl_add_u64 v[228:229], s[46:47], 0, v[130:131]
	global_load_lds_dwordx4 v[224:225], off
	v_lshl_add_u64 v[224:225], s[56:57], 0, v[128:129]
	s_add_i32 m0, s58, 0x2000
	s_nop 0
	global_load_lds_dwordx4 v[224:225], off
	v_lshl_add_u64 v[224:225], s[46:47], 0, v[134:135]
	s_mov_b32 m0, s33
	s_nop 0
	global_load_lds_dwordx4 v[224:225], off
	s_mov_b32 m0, s34
	s_nop 0
	global_load_lds_dwordx4 v[228:229], off
	s_cmp_eq_u32 s101, 0
	s_cbranch_scc1 .Lxw_p10_2s
	s_waitcnt vmcnt(16)
	s_mov_b32 s101, 0
	s_branch .Lxw_p10_2j

.Lxw_p10_2j:
	s_waitcnt lgkmcnt(0)
	s_barrier
	s_setprio 1
	s_waitcnt lgkmcnt(0)
	v_mfma_f32_16x16x32_bf16 v[60:63], v[156:159], v[188:191], v[60:63]
	v_mfma_f32_16x16x32_bf16 v[56:59], v[164:167], v[188:191], v[56:59]
	v_mfma_f32_16x16x32_bf16 v[44:47], v[156:159], v[198:201], v[44:47]
	v_mfma_f32_16x16x32_bf16 v[40:43], v[164:167], v[198:201], v[40:43]
	v_mfma_f32_16x16x32_bf16 v[28:31], v[156:159], v[206:209], v[28:31]
	v_mfma_f32_16x16x32_bf16 v[24:27], v[164:167], v[206:209], v[24:27]
	v_mfma_f32_16x16x32_bf16 v[12:15], v[156:159], v[214:217], v[12:15]
	v_mfma_f32_16x16x32_bf16 v[8:11], v[164:167], v[214:217], v[8:11]
	v_mfma_f32_16x16x32_bf16 v[60:63], v[160:163], v[194:197], v[60:63]
	v_mfma_f32_16x16x32_bf16 v[56:59], v[168:171], v[194:197], v[56:59]
	v_mfma_f32_16x16x32_bf16 v[44:47], v[160:163], v[202:205], v[44:47]
	v_mfma_f32_16x16x32_bf16 v[40:43], v[168:171], v[202:205], v[40:43]
	v_mfma_f32_16x16x32_bf16 v[28:31], v[160:163], v[210:213], v[28:31]
	v_mfma_f32_16x16x32_bf16 v[24:27], v[168:171], v[210:213], v[24:27]
	v_mfma_f32_16x16x32_bf16 v[12:15], v[160:163], v[218:221], v[12:15]
	v_mfma_f32_16x16x32_bf16 v[8:11], v[168:171], v[218:221], v[8:11]
	v_mfma_f32_16x16x32_bf16 v[52:55], v[172:175], v[188:191], v[52:55]
	v_mfma_f32_16x16x32_bf16 v[48:51], v[180:183], v[188:191], v[48:51]
	v_mfma_f32_16x16x32_bf16 v[36:39], v[172:175], v[198:201], v[36:39]
	v_mfma_f32_16x16x32_bf16 v[32:35], v[180:183], v[198:201], v[32:35]
	v_mfma_f32_16x16x32_bf16 v[20:23], v[172:175], v[206:209], v[20:23]
	v_mfma_f32_16x16x32_bf16 v[16:19], v[180:183], v[206:209], v[16:19]
	v_mfma_f32_16x16x32_bf16 v[4:7], v[172:175], v[214:217], v[4:7]
	v_mfma_f32_16x16x32_bf16 v[0:3], v[180:183], v[214:217], v[0:3]
	v_mfma_f32_16x16x32_bf16 v[52:55], v[176:179], v[194:197], v[52:55]
	v_mfma_f32_16x16x32_bf16 v[48:51], v[184:187], v[194:197], v[48:51]
	v_mfma_f32_16x16x32_bf16 v[36:39], v[176:179], v[202:205], v[36:39]
	v_mfma_f32_16x16x32_bf16 v[32:35], v[184:187], v[202:205], v[32:35]
	v_mfma_f32_16x16x32_bf16 v[20:23], v[176:179], v[210:213], v[20:23]
	v_mfma_f32_16x16x32_bf16 v[16:19], v[184:187], v[210:213], v[16:19]
	v_mfma_f32_16x16x32_bf16 v[4:7], v[176:179], v[218:221], v[4:7]
	v_mfma_f32_16x16x32_bf16 v[0:3], v[184:187], v[218:221], v[0:3]
	s_setprio 0
	s_barrier
	s_add_i32 s56, 0, 0x18000
	v_add_u32_e32 v136, s56, v151
	s_add_i32 s57, 0, 0x1c000
	ds_read_b128 v[156:159], v136
	ds_read_b128 v[160:163], v136 offset:1024
	ds_read_b128 v[164:167], v136 offset:2048
	ds_read_b128 v[168:171], v136 offset:3072
	v_add_u32_e32 v136, s57, v151
	ds_read_b128 v[172:175], v136
	ds_read_b128 v[176:179], v136 offset:1024
	ds_read_b128 v[180:183], v136 offset:2048
	ds_read_b128 v[184:187], v136 offset:3072
	s_add_u32 s46, s46, 0x40000
	s_addc_u32 s47, s47, 0
	s_mov_b32 m0, s35
	v_lshl_add_u64 v[230:231], s[46:47], 0, v[134:135]
	ds_read_b128 v[188:191], v155 offset:32768
	ds_read_b128 v[194:197], v155 offset:33792
	ds_read_b128 v[198:201], v155 offset:34816
	ds_read_b128 v[202:205], v155 offset:35840
	ds_read_b128 v[206:209], v155 offset:36864
	ds_read_b128 v[210:213], v155 offset:37888
	ds_read_b128 v[214:217], v155 offset:38912
	ds_read_b128 v[218:221], v155 offset:39936
	global_load_lds_dwordx4 v[230:231], off
	v_lshl_add_u64 v[230:231], s[46:47], 0, v[130:131]
	s_mov_b32 m0, s39
	s_nop 0
	global_load_lds_dwordx4 v[230:231], off
	s_waitcnt vmcnt(8)
	s_waitcnt lgkmcnt(0)
	s_barrier
	s_setprio 1
	s_waitcnt lgkmcnt(0)
	v_mfma_f32_16x16x32_bf16 v[124:127], v[156:159], v[188:191], v[124:127]
	v_mfma_f32_16x16x32_bf16 v[120:123], v[164:167], v[188:191], v[120:123]
	v_mfma_f32_16x16x32_bf16 v[108:111], v[156:159], v[198:201], v[108:111]
	v_mfma_f32_16x16x32_bf16 v[104:107], v[164:167], v[198:201], v[104:107]
	v_mfma_f32_16x16x32_bf16 v[92:95], v[156:159], v[206:209], v[92:95]
	v_mfma_f32_16x16x32_bf16 v[88:91], v[164:167], v[206:209], v[88:91]
	v_mfma_f32_16x16x32_bf16 v[76:79], v[156:159], v[214:217], v[76:79]
	v_mfma_f32_16x16x32_bf16 v[72:75], v[164:167], v[214:217], v[72:75]
	v_mfma_f32_16x16x32_bf16 v[124:127], v[160:163], v[194:197], v[124:127]
	v_mfma_f32_16x16x32_bf16 v[120:123], v[168:171], v[194:197], v[120:123]
	v_mfma_f32_16x16x32_bf16 v[108:111], v[160:163], v[202:205], v[108:111]
	v_mfma_f32_16x16x32_bf16 v[104:107], v[168:171], v[202:205], v[104:107]
	v_mfma_f32_16x16x32_bf16 v[92:95], v[160:163], v[210:213], v[92:95]
	v_mfma_f32_16x16x32_bf16 v[88:91], v[168:171], v[210:213], v[88:91]
	v_mfma_f32_16x16x32_bf16 v[76:79], v[160:163], v[218:221], v[76:79]
	v_mfma_f32_16x16x32_bf16 v[72:75], v[168:171], v[218:221], v[72:75]
	v_mfma_f32_16x16x32_bf16 v[116:119], v[172:175], v[188:191], v[116:119]
	v_mfma_f32_16x16x32_bf16 v[112:115], v[180:183], v[188:191], v[112:115]
	v_mfma_f32_16x16x32_bf16 v[100:103], v[172:175], v[198:201], v[100:103]
	v_mfma_f32_16x16x32_bf16 v[96:99], v[180:183], v[198:201], v[96:99]
	v_mfma_f32_16x16x32_bf16 v[84:87], v[172:175], v[206:209], v[84:87]
	v_mfma_f32_16x16x32_bf16 v[80:83], v[180:183], v[206:209], v[80:83]
	v_mfma_f32_16x16x32_bf16 v[68:71], v[172:175], v[214:217], v[68:71]
	v_mfma_f32_16x16x32_bf16 v[64:67], v[180:183], v[214:217], v[64:67]
	v_mfma_f32_16x16x32_bf16 v[116:119], v[176:179], v[194:197], v[116:119]
	v_mfma_f32_16x16x32_bf16 v[112:115], v[184:187], v[194:197], v[112:115]
	v_mfma_f32_16x16x32_bf16 v[100:103], v[176:179], v[202:205], v[100:103]
	v_mfma_f32_16x16x32_bf16 v[96:99], v[184:187], v[202:205], v[96:99]
	v_mfma_f32_16x16x32_bf16 v[84:87], v[176:179], v[210:213], v[84:87]
	v_mfma_f32_16x16x32_bf16 v[80:83], v[184:187], v[210:213], v[80:83]
	v_mfma_f32_16x16x32_bf16 v[68:71], v[176:179], v[218:221], v[68:71]
	v_mfma_f32_16x16x32_bf16 v[64:67], v[184:187], v[218:221], v[64:67]
	s_setprio 0
	s_barrier
	s_add_i32 s46, s56, s2
	v_lshl_add_u64 v[148:149], v[148:149], 0, s[12:13]
	s_mov_b32 m0, s46
	ds_read_b128 v[188:191], v155 offset:49152
	ds_read_b128 v[194:197], v155 offset:50176
	ds_read_b128 v[198:201], v155 offset:51200
	ds_read_b128 v[202:205], v155 offset:52224
	ds_read_b128 v[206:209], v155 offset:53248
	ds_read_b128 v[210:213], v155 offset:54272
	ds_read_b128 v[214:217], v155 offset:55296
	ds_read_b128 v[218:221], v155 offset:56320
	global_load_lds_dwordx4 v[148:149], off
	s_add_i32 m0, s46, 0x2000
	s_add_u32 s44, s44, 0x40080
	v_lshl_add_u64 v[148:149], v[222:223], 0, s[12:13]
	s_addc_u32 s45, s45, 0
	s_add_i32 s46, s57, s2
	global_load_lds_dwordx4 v[148:149], off
	v_lshl_add_u64 v[148:149], s[44:45], 0, v[132:133]
	s_mov_b32 m0, s46
	s_nop 0
	global_load_lds_dwordx4 v[148:149], off
	v_lshl_add_u64 v[148:149], s[44:45], 0, v[128:129]
	s_add_i32 m0, s46, 0x2000
	s_nop 0
	global_load_lds_dwordx4 v[148:149], off
	v_lshl_add_u64 v[148:149], v[224:225], 0, s[12:13]
	s_mov_b32 m0, s48
	s_nop 0
	global_load_lds_dwordx4 v[148:149], off
	v_lshl_add_u64 v[148:149], v[228:229], 0, s[12:13]
	s_mov_b32 m0, s49
	s_nop 0
	global_load_lds_dwordx4 v[148:149], off
	s_waitcnt vmcnt(8)
	s_waitcnt lgkmcnt(0)
	s_barrier
	s_setprio 1
	s_waitcnt lgkmcnt(0)
	v_mfma_f32_16x16x32_bf16 v[60:63], v[156:159], v[188:191], v[60:63]
	v_mfma_f32_16x16x32_bf16 v[56:59], v[164:167], v[188:191], v[56:59]
	v_mfma_f32_16x16x32_bf16 v[44:47], v[156:159], v[198:201], v[44:47]
	v_mfma_f32_16x16x32_bf16 v[40:43], v[164:167], v[198:201], v[40:43]
	v_mfma_f32_16x16x32_bf16 v[28:31], v[156:159], v[206:209], v[28:31]
	v_mfma_f32_16x16x32_bf16 v[24:27], v[164:167], v[206:209], v[24:27]
	v_mfma_f32_16x16x32_bf16 v[12:15], v[156:159], v[214:217], v[12:15]
	v_mfma_f32_16x16x32_bf16 v[8:11], v[164:167], v[214:217], v[8:11]
	v_mfma_f32_16x16x32_bf16 v[60:63], v[160:163], v[194:197], v[60:63]
	v_mfma_f32_16x16x32_bf16 v[56:59], v[168:171], v[194:197], v[56:59]
	v_mfma_f32_16x16x32_bf16 v[44:47], v[160:163], v[202:205], v[44:47]
	v_mfma_f32_16x16x32_bf16 v[40:43], v[168:171], v[202:205], v[40:43]
	v_mfma_f32_16x16x32_bf16 v[28:31], v[160:163], v[210:213], v[28:31]
	v_mfma_f32_16x16x32_bf16 v[24:27], v[168:171], v[210:213], v[24:27]
	v_mfma_f32_16x16x32_bf16 v[12:15], v[160:163], v[218:221], v[12:15]
	v_mfma_f32_16x16x32_bf16 v[8:11], v[168:171], v[218:221], v[8:11]
	v_mfma_f32_16x16x32_bf16 v[52:55], v[172:175], v[188:191], v[52:55]
	v_mfma_f32_16x16x32_bf16 v[48:51], v[180:183], v[188:191], v[48:51]
	v_mfma_f32_16x16x32_bf16 v[36:39], v[172:175], v[198:201], v[36:39]
	v_mfma_f32_16x16x32_bf16 v[32:35], v[180:183], v[198:201], v[32:35]
	v_mfma_f32_16x16x32_bf16 v[20:23], v[172:175], v[206:209], v[20:23]
	v_mfma_f32_16x16x32_bf16 v[16:19], v[180:183], v[206:209], v[16:19]
	v_mfma_f32_16x16x32_bf16 v[4:7], v[172:175], v[214:217], v[4:7]
	v_mfma_f32_16x16x32_bf16 v[0:3], v[180:183], v[214:217], v[0:3]
	v_mfma_f32_16x16x32_bf16 v[52:55], v[176:179], v[194:197], v[52:55]
	v_mfma_f32_16x16x32_bf16 v[48:51], v[184:187], v[194:197], v[48:51]
	v_mfma_f32_16x16x32_bf16 v[36:39], v[176:179], v[202:205], v[36:39]
	v_mfma_f32_16x16x32_bf16 v[32:35], v[184:187], v[202:205], v[32:35]
	v_mfma_f32_16x16x32_bf16 v[20:23], v[176:179], v[210:213], v[20:23]
	v_mfma_f32_16x16x32_bf16 v[16:19], v[184:187], v[210:213], v[16:19]
	v_mfma_f32_16x16x32_bf16 v[4:7], v[176:179], v[218:221], v[4:7]
	v_mfma_f32_16x16x32_bf16 v[0:3], v[184:187], v[218:221], v[0:3]
	s_setprio 0
	s_barrier
	s_add_i32 s55, s55, 2
	s_add_u32 s42, s42, 0x100
	s_addc_u32 s43, s43, 0
	s_add_u32 s27, s27, 0x100
	s_addc_u32 s29, s29, 0
	s_cmp_gt_u32 s55, 13
	s_cbranch_scc0 .LBB0_1101
	s_and_b64 vcc, exec, s[24:25]
	s_cbranch_vccz .LBB0_1104
	s_barrier
.LBB0_1104:
	v_add_u32_e32 v136, s40, v152
	v_ashrrev_i32_e32 v148, 1, v136
	v_and_b32_e32 v148, 0xffffff80, v148
	v_ashrrev_i32_e32 v149, 31, v148
	v_and_b32_e32 v136, 0x7f, v136
	v_lshl_add_u64 v[148:149], v[148:149], 1, s[20:21]
	v_lshlrev_b32_e32 v136, 1, v136
	v_lshl_add_u64 v[148:149], v[148:149], 0, v[136:137]
	v_mul_f32_e32 v136, 0xbfb8aa3b, v124
	v_exp_f32_e32 v136, v136
	v_mul_f32_e32 v157, 0xbfb8aa3b, v120
	v_mul_f32_e32 v158, 0xbfb8aa3b, v125
	v_exp_f32_e32 v157, v157
	v_exp_f32_e32 v159, v158
	v_add_f32_e32 v136, 1.0, v136
	v_rcp_f32_e32 v158, v136
	v_add_f32_e32 v136, 1.0, v157
	v_add_f32_e32 v157, 1.0, v159
	v_rcp_f32_e32 v159, v157
	v_mul_f32_e32 v157, 0xbfb8aa3b, v121
	v_exp_f32_e32 v157, v157
	v_rcp_f32_e32 v160, v136
	v_pk_mul_f32 v[124:125], v[124:125], v[158:159]
	v_mul_f32_e32 v136, 0xbfb8aa3b, v127
	v_pk_mul_f32 v[116:117], v[124:125], v[116:117]
	v_add_f32_e32 v124, 1.0, v157
	v_mul_f32_e32 v125, 0xbfb8aa3b, v122
	v_rcp_f32_e32 v161, v124
	v_mul_f32_e32 v124, 0xbfb8aa3b, v126
	v_exp_f32_e32 v125, v125
	v_exp_f32_e32 v124, v124
	v_exp_f32_e32 v136, v136
	v_mul_f32_e32 v157, 0xbfb8aa3b, v123
	v_exp_f32_e32 v157, v157
	v_add_f32_e32 v125, 1.0, v125
	v_add_f32_e32 v124, 1.0, v124
	v_rcp_f32_e32 v158, v125
	v_add_f32_e32 v125, 1.0, v136
	v_rcp_f32_e32 v124, v124
	v_rcp_f32_e32 v125, v125
	v_add_f32_e32 v136, 1.0, v157
	v_rcp_f32_e32 v159, v136
	v_pk_mul_f32 v[120:121], v[120:121], v[160:161]
	v_add_u32_e32 v156, s38, v150
	v_pk_mul_f32 v[120:121], v[120:121], v[112:113]
	v_pk_mul_f32 v[112:113], v[126:127], v[124:125]
	s_andn2_b64 vcc, exec, s[0:1]
	v_pk_mul_f32 v[118:119], v[112:113], v[118:119]
	v_pk_mul_f32 v[112:113], v[122:123], v[158:159]
	s_mov_b64 s[0:1], -1
	v_pk_mul_f32 v[122:123], v[112:113], v[114:115]
	v_cvt_pk_bf16_f32 v112, v116, v117
	v_cvt_pk_bf16_f32 v113, v118, v119
	v_cvt_pk_bf16_f32 v114, v120, v121
	v_cvt_pk_bf16_f32 v115, v122, v123
	v_mad_i64_i32 v[116:117], s[42:43], v156, s54, v[148:149]
	global_store_dwordx4 v[116:117], v[112:115], off nt
	v_add_u32_e32 v116, 16, v156
	s_nop 0
	v_mul_f32_e32 v112, 0xbfb8aa3b, v108
	v_mul_f32_e32 v113, 0xbfb8aa3b, v104
	v_mul_f32_e32 v114, 0xbfb8aa3b, v109
	v_exp_f32_e32 v112, v112
	v_exp_f32_e32 v113, v113
	v_exp_f32_e32 v114, v114
	v_add_f32_e32 v112, 1.0, v112
	v_add_f32_e32 v115, 1.0, v113
	v_add_f32_e32 v113, 1.0, v114
	v_rcp_f32_e32 v112, v112
	v_rcp_f32_e32 v113, v113
	v_mul_f32_e32 v114, 0xbfb8aa3b, v105
	v_exp_f32_e32 v117, v114
	v_rcp_f32_e32 v114, v115
	v_pk_mul_f32 v[108:109], v[108:109], v[112:113]
	v_mul_f32_e32 v112, 0xbfb8aa3b, v111
	v_pk_mul_f32 v[100:101], v[108:109], v[100:101]
	v_add_f32_e32 v108, 1.0, v117
	v_rcp_f32_e32 v115, v108
	v_mul_f32_e32 v109, 0xbfb8aa3b, v106
	v_mul_f32_e32 v108, 0xbfb8aa3b, v110
	v_exp_f32_e32 v109, v109
	v_exp_f32_e32 v108, v108
	v_exp_f32_e32 v113, v112
	v_mul_f32_e32 v112, 0xbfb8aa3b, v107
	v_pk_mul_f32 v[104:105], v[104:105], v[114:115]
	v_exp_f32_e32 v114, v112
	v_add_f32_e32 v109, 1.0, v109
	v_add_f32_e32 v108, 1.0, v108
	v_rcp_f32_e32 v112, v109
	v_add_f32_e32 v109, 1.0, v113
	v_rcp_f32_e32 v108, v108
	v_rcp_f32_e32 v109, v109
	v_add_f32_e32 v113, 1.0, v114
	v_rcp_f32_e32 v113, v113
	v_pk_mul_f32 v[104:105], v[104:105], v[96:97]
	v_pk_mul_f32 v[96:97], v[110:111], v[108:109]
	s_nop 0
	v_pk_mul_f32 v[102:103], v[96:97], v[102:103]
	v_pk_mul_f32 v[96:97], v[106:107], v[112:113]
	s_nop 0
	v_pk_mul_f32 v[106:107], v[96:97], v[98:99]
	v_cvt_pk_bf16_f32 v96, v100, v101
	v_cvt_pk_bf16_f32 v97, v102, v103
	v_cvt_pk_bf16_f32 v98, v104, v105
	v_cvt_pk_bf16_f32 v99, v106, v107
	v_mad_i64_i32 v[100:101], s[42:43], v116, s54, v[148:149]
	global_store_dwordx4 v[100:101], v[96:99], off nt
	v_add_u32_e32 v100, 32, v156
	s_nop 0
	v_mul_f32_e32 v96, 0xbfb8aa3b, v92
	v_mul_f32_e32 v97, 0xbfb8aa3b, v88
	v_mul_f32_e32 v98, 0xbfb8aa3b, v93
	v_exp_f32_e32 v96, v96
	v_exp_f32_e32 v97, v97
	v_exp_f32_e32 v98, v98
	v_add_f32_e32 v96, 1.0, v96
	v_add_f32_e32 v99, 1.0, v97
	v_add_f32_e32 v97, 1.0, v98
	v_rcp_f32_e32 v96, v96
	v_rcp_f32_e32 v97, v97
	v_mul_f32_e32 v98, 0xbfb8aa3b, v89
	v_exp_f32_e32 v101, v98
	v_rcp_f32_e32 v98, v99
	v_pk_mul_f32 v[92:93], v[92:93], v[96:97]
	v_mul_f32_e32 v96, 0xbfb8aa3b, v95
	v_pk_mul_f32 v[84:85], v[92:93], v[84:85]
	v_add_f32_e32 v92, 1.0, v101
	v_rcp_f32_e32 v99, v92
	v_mul_f32_e32 v93, 0xbfb8aa3b, v90
	v_mul_f32_e32 v92, 0xbfb8aa3b, v94
	v_exp_f32_e32 v93, v93
	v_exp_f32_e32 v92, v92
	v_exp_f32_e32 v97, v96
	v_mul_f32_e32 v96, 0xbfb8aa3b, v91
	v_pk_mul_f32 v[88:89], v[88:89], v[98:99]
	v_exp_f32_e32 v98, v96
	v_add_f32_e32 v93, 1.0, v93
	v_add_f32_e32 v92, 1.0, v92
	v_rcp_f32_e32 v96, v93
	v_add_f32_e32 v93, 1.0, v97
	v_rcp_f32_e32 v92, v92
	v_rcp_f32_e32 v93, v93
	v_add_f32_e32 v97, 1.0, v98
	v_rcp_f32_e32 v97, v97
	v_pk_mul_f32 v[88:89], v[88:89], v[80:81]
	v_pk_mul_f32 v[80:81], v[94:95], v[92:93]
	s_nop 0
	v_pk_mul_f32 v[86:87], v[80:81], v[86:87]
	v_pk_mul_f32 v[80:81], v[90:91], v[96:97]
	s_nop 0
	v_pk_mul_f32 v[90:91], v[80:81], v[82:83]
	v_cvt_pk_bf16_f32 v80, v84, v85
	v_cvt_pk_bf16_f32 v81, v86, v87
	v_cvt_pk_bf16_f32 v82, v88, v89
	v_cvt_pk_bf16_f32 v83, v90, v91
	v_mad_i64_i32 v[84:85], s[42:43], v100, s54, v[148:149]
	global_store_dwordx4 v[84:85], v[80:83], off nt
	v_add_u32_e32 v84, 48, v156
	s_nop 0
	v_mul_f32_e32 v80, 0xbfb8aa3b, v76
	v_mul_f32_e32 v81, 0xbfb8aa3b, v72
	v_mul_f32_e32 v82, 0xbfb8aa3b, v77
	v_exp_f32_e32 v80, v80
	v_exp_f32_e32 v81, v81
	v_exp_f32_e32 v82, v82
	v_add_f32_e32 v80, 1.0, v80
	v_add_f32_e32 v83, 1.0, v81
	v_add_f32_e32 v81, 1.0, v82
	v_rcp_f32_e32 v80, v80
	v_rcp_f32_e32 v81, v81
	v_mul_f32_e32 v82, 0xbfb8aa3b, v73
	v_exp_f32_e32 v85, v82
	v_rcp_f32_e32 v82, v83
	v_pk_mul_f32 v[76:77], v[76:77], v[80:81]
	v_mul_f32_e32 v80, 0xbfb8aa3b, v79
	v_pk_mul_f32 v[68:69], v[76:77], v[68:69]
	v_add_f32_e32 v76, 1.0, v85
	v_rcp_f32_e32 v83, v76
	v_mul_f32_e32 v77, 0xbfb8aa3b, v74
	v_mul_f32_e32 v76, 0xbfb8aa3b, v78
	v_exp_f32_e32 v77, v77
	v_exp_f32_e32 v76, v76
	v_exp_f32_e32 v81, v80
	v_mul_f32_e32 v80, 0xbfb8aa3b, v75
	v_pk_mul_f32 v[72:73], v[72:73], v[82:83]
	v_exp_f32_e32 v82, v80
	v_add_f32_e32 v77, 1.0, v77
	v_add_f32_e32 v76, 1.0, v76
	v_rcp_f32_e32 v80, v77
	v_add_f32_e32 v77, 1.0, v81
	v_rcp_f32_e32 v76, v76
	v_rcp_f32_e32 v77, v77
	v_add_f32_e32 v81, 1.0, v82
	v_rcp_f32_e32 v81, v81
	v_pk_mul_f32 v[72:73], v[72:73], v[64:65]
	v_pk_mul_f32 v[64:65], v[78:79], v[76:77]
	s_nop 0
	v_pk_mul_f32 v[70:71], v[64:65], v[70:71]
	v_pk_mul_f32 v[64:65], v[74:75], v[80:81]
	s_nop 0
	v_pk_mul_f32 v[74:75], v[64:65], v[66:67]
	v_cvt_pk_bf16_f32 v64, v68, v69
	v_cvt_pk_bf16_f32 v65, v70, v71
	v_cvt_pk_bf16_f32 v66, v72, v73
	v_cvt_pk_bf16_f32 v67, v74, v75
	v_mad_i64_i32 v[68:69], s[42:43], v84, s54, v[148:149]
	global_store_dwordx4 v[68:69], v[64:67], off nt
	v_add_u32_e32 v68, 0x80, v156
	s_nop 0
	v_mul_f32_e32 v64, 0xbfb8aa3b, v60
	v_mul_f32_e32 v65, 0xbfb8aa3b, v56
	v_mul_f32_e32 v66, 0xbfb8aa3b, v61
	v_exp_f32_e32 v64, v64
	v_exp_f32_e32 v65, v65
	v_exp_f32_e32 v66, v66
	v_add_f32_e32 v64, 1.0, v64
	v_add_f32_e32 v67, 1.0, v65
	v_add_f32_e32 v65, 1.0, v66
	v_rcp_f32_e32 v64, v64
	v_rcp_f32_e32 v65, v65
	v_mul_f32_e32 v66, 0xbfb8aa3b, v57
	v_exp_f32_e32 v69, v66
	v_rcp_f32_e32 v66, v67
	v_pk_mul_f32 v[60:61], v[60:61], v[64:65]
	v_mul_f32_e32 v64, 0xbfb8aa3b, v63
	v_pk_mul_f32 v[52:53], v[60:61], v[52:53]
	v_add_f32_e32 v60, 1.0, v69
	v_rcp_f32_e32 v67, v60
	v_mul_f32_e32 v61, 0xbfb8aa3b, v58
	v_mul_f32_e32 v60, 0xbfb8aa3b, v62
	v_exp_f32_e32 v61, v61
	v_exp_f32_e32 v60, v60
	v_exp_f32_e32 v65, v64
	v_mul_f32_e32 v64, 0xbfb8aa3b, v59
	v_pk_mul_f32 v[56:57], v[56:57], v[66:67]
	v_exp_f32_e32 v66, v64
	v_add_f32_e32 v61, 1.0, v61
	v_add_f32_e32 v60, 1.0, v60
	v_rcp_f32_e32 v64, v61
	v_add_f32_e32 v61, 1.0, v65
	v_rcp_f32_e32 v60, v60
	v_rcp_f32_e32 v61, v61
	v_add_f32_e32 v65, 1.0, v66
	v_rcp_f32_e32 v65, v65
	v_pk_mul_f32 v[56:57], v[56:57], v[48:49]
	v_pk_mul_f32 v[48:49], v[62:63], v[60:61]
	s_nop 0
	v_pk_mul_f32 v[54:55], v[48:49], v[54:55]
	v_pk_mul_f32 v[48:49], v[58:59], v[64:65]
	s_nop 0
	v_pk_mul_f32 v[58:59], v[48:49], v[50:51]
	v_cvt_pk_bf16_f32 v48, v52, v53
	v_cvt_pk_bf16_f32 v49, v54, v55
	v_cvt_pk_bf16_f32 v50, v56, v57
	v_cvt_pk_bf16_f32 v51, v58, v59
	v_mad_i64_i32 v[52:53], s[42:43], v68, s54, v[148:149]
	global_store_dwordx4 v[52:53], v[48:51], off nt
	v_add_u32_e32 v52, 0x90, v156
	s_nop 0
	v_mul_f32_e32 v48, 0xbfb8aa3b, v44
	v_mul_f32_e32 v49, 0xbfb8aa3b, v40
	v_mul_f32_e32 v50, 0xbfb8aa3b, v45
	v_exp_f32_e32 v48, v48
	v_exp_f32_e32 v49, v49
	v_exp_f32_e32 v50, v50
	v_add_f32_e32 v48, 1.0, v48
	v_add_f32_e32 v51, 1.0, v49
	v_add_f32_e32 v49, 1.0, v50
	v_rcp_f32_e32 v48, v48
	v_rcp_f32_e32 v49, v49
	v_mul_f32_e32 v50, 0xbfb8aa3b, v41
	v_exp_f32_e32 v53, v50
	v_rcp_f32_e32 v50, v51
	v_pk_mul_f32 v[44:45], v[44:45], v[48:49]
	v_mul_f32_e32 v48, 0xbfb8aa3b, v47
	v_pk_mul_f32 v[36:37], v[44:45], v[36:37]
	v_add_f32_e32 v44, 1.0, v53
	v_rcp_f32_e32 v51, v44
	v_mul_f32_e32 v45, 0xbfb8aa3b, v42
	v_mul_f32_e32 v44, 0xbfb8aa3b, v46
	v_exp_f32_e32 v45, v45
	v_exp_f32_e32 v44, v44
	v_exp_f32_e32 v49, v48
	v_mul_f32_e32 v48, 0xbfb8aa3b, v43
	v_pk_mul_f32 v[40:41], v[40:41], v[50:51]
	v_exp_f32_e32 v50, v48
	v_add_f32_e32 v45, 1.0, v45
	v_add_f32_e32 v44, 1.0, v44
	v_rcp_f32_e32 v48, v45
	v_add_f32_e32 v45, 1.0, v49
	v_rcp_f32_e32 v44, v44
	v_rcp_f32_e32 v45, v45
	v_add_f32_e32 v49, 1.0, v50
	v_rcp_f32_e32 v49, v49
	v_pk_mul_f32 v[40:41], v[40:41], v[32:33]
	v_pk_mul_f32 v[32:33], v[46:47], v[44:45]
	s_nop 0
	v_pk_mul_f32 v[38:39], v[32:33], v[38:39]
	v_pk_mul_f32 v[32:33], v[42:43], v[48:49]
	s_nop 0
	v_pk_mul_f32 v[42:43], v[32:33], v[34:35]
	v_cvt_pk_bf16_f32 v32, v36, v37
	v_cvt_pk_bf16_f32 v33, v38, v39
	v_cvt_pk_bf16_f32 v34, v40, v41
	v_cvt_pk_bf16_f32 v35, v42, v43
	v_mad_i64_i32 v[36:37], s[42:43], v52, s54, v[148:149]
	global_store_dwordx4 v[36:37], v[32:35], off nt
	v_add_u32_e32 v36, 0xa0, v156
	s_nop 0
	v_mul_f32_e32 v32, 0xbfb8aa3b, v28
	v_mul_f32_e32 v33, 0xbfb8aa3b, v24
	v_mul_f32_e32 v34, 0xbfb8aa3b, v29
	v_exp_f32_e32 v32, v32
	v_exp_f32_e32 v33, v33
	v_exp_f32_e32 v34, v34
	v_add_f32_e32 v32, 1.0, v32
	v_add_f32_e32 v35, 1.0, v33
	v_add_f32_e32 v33, 1.0, v34
	v_rcp_f32_e32 v32, v32
	v_rcp_f32_e32 v33, v33
	v_mul_f32_e32 v34, 0xbfb8aa3b, v25
	v_exp_f32_e32 v37, v34
	v_rcp_f32_e32 v34, v35
	v_pk_mul_f32 v[28:29], v[28:29], v[32:33]
	v_mul_f32_e32 v32, 0xbfb8aa3b, v31
	v_pk_mul_f32 v[20:21], v[28:29], v[20:21]
	v_add_f32_e32 v28, 1.0, v37
	v_rcp_f32_e32 v35, v28
	v_mul_f32_e32 v29, 0xbfb8aa3b, v26
	v_mul_f32_e32 v28, 0xbfb8aa3b, v30
	v_exp_f32_e32 v29, v29
	v_exp_f32_e32 v28, v28
	v_exp_f32_e32 v33, v32
	v_mul_f32_e32 v32, 0xbfb8aa3b, v27
	v_pk_mul_f32 v[24:25], v[24:25], v[34:35]
	v_exp_f32_e32 v34, v32
	v_add_f32_e32 v29, 1.0, v29
	v_add_f32_e32 v28, 1.0, v28
	v_rcp_f32_e32 v32, v29
	v_add_f32_e32 v29, 1.0, v33
	v_rcp_f32_e32 v28, v28
	v_rcp_f32_e32 v29, v29
	v_add_f32_e32 v33, 1.0, v34
	v_rcp_f32_e32 v33, v33
	v_pk_mul_f32 v[24:25], v[24:25], v[16:17]
	v_pk_mul_f32 v[16:17], v[30:31], v[28:29]
	s_nop 0
	v_pk_mul_f32 v[22:23], v[16:17], v[22:23]
	v_pk_mul_f32 v[16:17], v[26:27], v[32:33]
	s_nop 0
	v_pk_mul_f32 v[26:27], v[16:17], v[18:19]
	v_cvt_pk_bf16_f32 v16, v20, v21
	v_cvt_pk_bf16_f32 v17, v22, v23
	v_cvt_pk_bf16_f32 v18, v24, v25
	v_cvt_pk_bf16_f32 v19, v26, v27
	v_mad_i64_i32 v[20:21], s[42:43], v36, s54, v[148:149]
	global_store_dwordx4 v[20:21], v[16:19], off nt
	v_add_u32_e32 v20, 0xb0, v156
	s_nop 0
	v_mul_f32_e32 v16, 0xbfb8aa3b, v12
	v_mul_f32_e32 v17, 0xbfb8aa3b, v8
	v_mul_f32_e32 v18, 0xbfb8aa3b, v13
	v_exp_f32_e32 v16, v16
	v_exp_f32_e32 v17, v17
	v_exp_f32_e32 v18, v18
	v_add_f32_e32 v16, 1.0, v16
	v_add_f32_e32 v19, 1.0, v17
	v_add_f32_e32 v17, 1.0, v18
	v_rcp_f32_e32 v16, v16
	v_rcp_f32_e32 v17, v17
	v_mul_f32_e32 v18, 0xbfb8aa3b, v9
	v_exp_f32_e32 v21, v18
	v_rcp_f32_e32 v18, v19
	v_pk_mul_f32 v[12:13], v[12:13], v[16:17]
	v_mul_f32_e32 v16, 0xbfb8aa3b, v15
	v_pk_mul_f32 v[4:5], v[12:13], v[4:5]
	v_add_f32_e32 v12, 1.0, v21
	v_rcp_f32_e32 v19, v12
	v_mul_f32_e32 v13, 0xbfb8aa3b, v10
	v_mul_f32_e32 v12, 0xbfb8aa3b, v14
	v_exp_f32_e32 v13, v13
	v_exp_f32_e32 v12, v12
	v_exp_f32_e32 v17, v16
	v_mul_f32_e32 v16, 0xbfb8aa3b, v11
	v_pk_mul_f32 v[8:9], v[8:9], v[18:19]
	v_exp_f32_e32 v18, v16
	v_add_f32_e32 v13, 1.0, v13
	v_add_f32_e32 v12, 1.0, v12
	v_rcp_f32_e32 v16, v13
	v_add_f32_e32 v13, 1.0, v17
	v_rcp_f32_e32 v12, v12
	v_rcp_f32_e32 v13, v13
	v_add_f32_e32 v17, 1.0, v18
	v_rcp_f32_e32 v17, v17
	v_pk_mul_f32 v[8:9], v[8:9], v[0:1]
	v_pk_mul_f32 v[0:1], v[14:15], v[12:13]
	s_nop 0
	v_pk_mul_f32 v[6:7], v[0:1], v[6:7]
	v_pk_mul_f32 v[0:1], v[10:11], v[16:17]
	s_nop 0
	v_pk_mul_f32 v[10:11], v[0:1], v[2:3]
	v_cvt_pk_bf16_f32 v0, v4, v5
	v_cvt_pk_bf16_f32 v1, v6, v7
	v_cvt_pk_bf16_f32 v2, v8, v9
	v_cvt_pk_bf16_f32 v3, v10, v11
	v_mad_i64_i32 v[4:5], s[42:43], v20, s54, v[148:149]
	global_store_dwordx4 v[4:5], v[0:3], off nt
	s_mov_b32 s101, 1
	s_cbranch_vccnz .LBB0_1097
	s_andn2_b64 vcc, exec, s[8:9]
	s_cbranch_vccnz .LBB0_1096
	s_barrier
	s_branch .LBB0_1096
